# gqa QK segment: K-fragment ds_read pairs rotated over 2-3 register sets and issued 2-3 MFMA pairs ahead (was read,read,wait,mfma,mfma back to back)
# baseline (speedup 1.0000x reference)
; #define SBAR() __builtin_amdgcn_sched_barrier(0)
; #define KWRITE(b, src0, src1) do { if constexpr (ND0 == 4) { *(bf16x8*)(K_lds + (b) * SHM_K + KSWZ(kr, kcb)) = src0; } \
;     else { int kc = sc * 2; *(bf16x8*)(K_lds + (b) * SHM_K + KSWZ(sr, kc)) = src0; *(bf16x8*)(K_lds + (b) * SHM_K + KSWZ(32 + sr, kc)) = src1; } } while (0)
; #define SLOAD_B(k0) do { vs0b = *reinterpret_cast<const bf16x8*>(&Vh[(long)((k0) + sr) * LDK + sc]); vs1b = *reinterpret_cast<const bf16x8*>(&Vh[(long)((k0) + 32 + sr) * LDK + sc]); KLOAD(ks0b, ks1b, k0); } while (0)
; #define PSM(P0, P1, MN, AL) do { if constexpr (PRE) partialSM_pre(P0, P1, m_reg, AL, 11.541560327111707f); else partialSM(P0, P1, m_reg, MN, AL, C, thr_raw); } while (0)
; __device__ __forceinline__ void finishSM(f32x16& p0, f32x16& p1, float alpha, float& l_reg, bf16x8& pa0, bf16x8& pa1, bf16x8& pa2, bf16x8& pa3) {
; #pragma unroll
;   for (int r = 0; r < 16; ++r) p1[r] = __builtin_amdgcn_exp2f(p1[r]);
;   float ps = 0;
; #pragma unroll
;   for (int r = 0; r < 16; ++r) ps += p0[r];
; #pragma unroll
;   for (int r = 0; r < 16; ++r) ps += p1[r];
;   { auto rr = __builtin_amdgcn_permlane32_swap(__float_as_uint(ps), __float_as_uint(ps), false, false);
;     ps = __uint_as_float(rr[0]) + __uint_as_float(rr[1]); }
;   l_reg = l_reg * alpha + ps;
;     ...
;   PK4(p0, 0, pa0); PK4(p0, 8, pa1); PK4(p1, 0, pa2); PK4(p1, 8, pa3);
;     ...
; }
; template <int ND0>
; __device__ __forceinline__ void qkt(f32x16& p0, f32x16& p1, const char* Ks, const bf16x8* qr, int r32, int hi) {
;   p0 = f32x16{}; p1 = f32x16{};
; #pragma unroll
;   for (int d0 = 0; d0 < ND0; ++d0) { int cb = (d0 * 16 + hi * 8) * 2;
;     bf16x8 b0 = *reinterpret_cast<const bf16x8*>(Ks + KSWZ(r32, cb));
;     bf16x8 b1 = *reinterpret_cast<const bf16x8*>(Ks + KSWZ(32 + r32, cb));
;     p0 = __builtin_amdgcn_mfma_f32_32x32x16_bf16(b0, qr[d0], p0, 0, 0, 0);
;     p1 = __builtin_amdgcn_mfma_f32_32x32x16_bf16(b1, qr[d0], p1, 0, 0, 0); }
; }
; template <int ND0, int LDQ, int LDK, int LDO> ...
;     ...
;     SBAR(); qkt<ND0>(pB0, pB1, Kq1, qr, r32, hi);
;     finishSM(pA0, pA1, alA, l_reg, pa0, pa1, pa2, pa3); SBAR();
;     SLOAD_B((j + 2) * KVBLK); SBAR();
;     pv_d0(o, vb0, pa0, pa1, pa2, pa3); KWRITE(0, ks0a, ks1a); PSM(pB0, pB1, mnB, alB);
.LBB0_146:
	ds_read_b128 v[208:211], v200 offset:49152
	ds_read_b128 v[214:217], v200 offset:57344
	ds_read_b128 v[234:237], v202 offset:49152
	ds_read_b128 v[238:241], v202 offset:57344
	v_exp_f32_e32 v170, v64
	s_waitcnt lgkmcnt(4)
	v_mfma_f32_32x32x16_bf16 v[96:111], v[80:83], v[114:117], 0
	v_add_f32_e32 v64, v213, v176
	v_add_f32_e32 v64, v174, v64
	v_add_f32_e32 v64, v177, v64
	v_add_f32_e32 v64, v173, v64
	v_add_f32_e32 v64, v175, v64
	v_add_f32_e32 v64, v171, v64
	v_add_f32_e32 v64, v172, v64
	v_mfma_f32_32x32x16_bf16 v[80:95], v[84:87], v[114:117], 0
	v_add_f32_e32 v64, v167, v64
	v_add_f32_e32 v64, v169, v64
	v_add_f32_e32 v64, v166, v64
	v_add_f32_e32 v64, v168, v64
	v_add_f32_e32 v64, v163, v64
	v_add_f32_e32 v64, v165, v64
	v_add_f32_e32 v64, v162, v64
	s_waitcnt lgkmcnt(2)
	v_mfma_f32_32x32x16_bf16 v[96:111], v[208:211], v[122:125], v[96:111]
	v_exp_f32_e32 v212, v67
	v_add_f32_e32 v64, v164, v64
	v_add_f32_e32 v64, v170, v64
	v_exp_f32_e32 v218, v72
	v_exp_f32_e32 v219, v73
	v_exp_f32_e32 v220, v74
	v_exp_f32_e32 v221, v75
	v_mfma_f32_32x32x16_bf16 v[80:95], v[214:217], v[122:125], v[80:95]
	ds_read_b128 v[208:211], v201 offset:49152
	ds_read_b128 v[214:217], v201 offset:57344
	v_exp_f32_e32 v222, v76
	v_exp_f32_e32 v223, v77
	v_exp_f32_e32 v224, v78
	v_exp_f32_e32 v79, v79
	s_waitcnt lgkmcnt(2)
	v_mfma_f32_32x32x16_bf16 v[96:111], v[234:237], v[142:145], v[96:111]
	v_mfma_f32_32x32x16_bf16 v[80:95], v[238:241], v[142:145], v[80:95]
	ds_read_b128 v[234:237], v203 offset:49152
	ds_read_b128 v[238:241], v203 offset:57344
	s_waitcnt lgkmcnt(2)
	v_mfma_f32_32x32x16_bf16 v[96:111], v[208:211], v[138:141], v[96:111]
	v_mfma_f32_32x32x16_bf16 v[80:95], v[214:217], v[138:141], v[80:95]
	ds_read_b128 v[208:211], v204 offset:49152
	ds_read_b128 v[214:217], v204 offset:57344
	s_waitcnt lgkmcnt(2)
	v_mfma_f32_32x32x16_bf16 v[96:111], v[234:237], v[134:137], v[96:111]
	v_mfma_f32_32x32x16_bf16 v[80:95], v[238:241], v[134:137], v[80:95]
	ds_read_b128 v[234:237], v206 offset:49152
	ds_read_b128 v[238:241], v206 offset:57344
	s_waitcnt lgkmcnt(2)
	v_mfma_f32_32x32x16_bf16 v[96:111], v[208:211], v[130:133], v[96:111]
	v_mfma_f32_32x32x16_bf16 v[80:95], v[214:217], v[130:133], v[80:95]
	ds_read_b128 v[208:211], v205 offset:49152
	ds_read_b128 v[214:217], v205 offset:57344
	s_waitcnt lgkmcnt(2)
	v_mfma_f32_32x32x16_bf16 v[96:111], v[234:237], v[126:129], v[96:111]
	v_mfma_f32_32x32x16_bf16 v[80:95], v[238:241], v[126:129], v[80:95]
	s_waitcnt lgkmcnt(0)
	v_mfma_f32_32x32x16_bf16 v[96:111], v[208:211], v[118:121], v[96:111]
	v_exp_f32_e32 v210, v65
	v_exp_f32_e32 v211, v66
	v_add_f32_e32 v64, v210, v64
	v_add_f32_e32 v64, v211, v64
	v_add_f32_e32 v64, v212, v64
	v_mfma_f32_32x32x16_bf16 v[80:95], v[214:217], v[118:121], v[80:95]
	v_exp_f32_e32 v214, v68
	v_exp_f32_e32 v215, v69
	v_exp_f32_e32 v216, v70
	v_exp_f32_e32 v217, v71
	v_add_f32_e32 v64, v214, v64
	v_add_f32_e32 v64, v215, v64
	v_add_f32_e32 v64, v216, v64
	v_add_f32_e32 v64, v217, v64
	v_add_f32_e32 v64, v218, v64
	v_add_f32_e32 v64, v219, v64
	v_add_f32_e32 v64, v220, v64
	v_add_f32_e32 v64, v221, v64
	v_add_f32_e32 v64, v222, v64
	v_add_f32_e32 v64, v223, v64
	v_add_f32_e32 v64, v224, v64
	v_add_f32_e32 v208, v79, v64
	v_mov_b32_e32 v209, v208
	v_cvt_pk_bf16_f32 v64, v176, v213
	v_cvt_pk_bf16_f32 v65, v174, v177
	v_cvt_pk_bf16_f32 v66, v173, v175
	v_cvt_pk_bf16_f32 v67, v171, v172
	v_cvt_pk_bf16_f32 v68, v167, v169
	v_cvt_pk_bf16_f32 v69, v166, v168
	v_cvt_pk_bf16_f32 v70, v163, v165
	v_cvt_pk_bf16_f32 v71, v162, v164
	v_cvt_pk_bf16_f32 v72, v170, v210
	v_cvt_pk_bf16_f32 v73, v211, v212
	v_cvt_pk_bf16_f32 v74, v214, v215
	v_cvt_pk_bf16_f32 v75, v216, v217
	v_cvt_pk_bf16_f32 v76, v218, v219
	v_cvt_pk_bf16_f32 v77, v220, v221
	v_cvt_pk_bf16_f32 v78, v222, v223
	v_cvt_pk_bf16_f32 v79, v224, v79
	v_permlane32_swap_b32_e32 v208, v209
	v_permlane32_swap_b32_e32 v64, v66
	v_permlane32_swap_b32_e32 v65, v67
	v_permlane32_swap_b32_e32 v68, v70
	v_permlane32_swap_b32_e32 v69, v71
	v_permlane32_swap_b32_e32 v72, v74
	v_permlane32_swap_b32_e32 v73, v75
	v_permlane32_swap_b32_e32 v76, v78
	v_permlane32_swap_b32_e32 v77, v79
	s_mov_b32 s4, 0xfffb8000
	v_add_co_u32_e32 v166, vcc, s4, v188
	s_mov_b32 s4, 0xfffd0000
	s_nop 0
	v_addc_co_u32_e32 v167, vcc, -1, v189, vcc
	v_add_co_u32_e32 v174, vcc, s4, v188
	s_nop 1
	v_addc_co_u32_e32 v175, vcc, -1, v189, vcc
	global_load_dwordx4 v[162:165], v[166:167], off
	global_load_dwordx4 v[170:173], v[166:167], off offset:-512
	global_load_dwordx4 v[166:169], v[174:175], off
	global_load_dwordx4 v[174:177], v[174:175], off offset:-512
	v_cmp_neq_f32_e32 vcc, 0, v193
	ds_read_b64_tr_b16 v[210:211], v194 offset:0
	ds_read_b64_tr_b16 v[212:213], v194 offset:0x800
	ds_read_b64_tr_b16 v[214:215], v194 offset:0x1000
	ds_read_b64_tr_b16 v[216:217], v194 offset:0x1800
	ds_read_b64_tr_b16 v[218:219], v194 offset:0x2000
	ds_read_b64_tr_b16 v[220:221], v194 offset:0x2800
	ds_read_b64_tr_b16 v[222:223], v194 offset:0x3000
	ds_read_b64_tr_b16 v[224:225], v194 offset:0x3800
	s_cbranch_vccnz .LBB0_163

; #define SBAR() __builtin_amdgcn_sched_barrier(0)
; #define SLOAD_A(k0) do { vs0a = *reinterpret_cast<const bf16x8*>(&Vh[(long)((k0) + sr) * LDK + sc]); vs1a = *reinterpret_cast<const bf16x8*>(&Vh[(long)((k0) + 32 + sr) * LDK + sc]); KLOAD(ks0a, ks1a, k0); } while (0)
; __device__ __forceinline__ void finishSM(f32x16& p0, f32x16& p1, float alpha, float& l_reg, bf16x8& pa0, bf16x8& pa1, bf16x8& pa2, bf16x8& pa3) {
; #pragma unroll
;   for (int r = 0; r < 16; ++r) p1[r] = __builtin_amdgcn_exp2f(p1[r]);
;   float ps = 0;
; #pragma unroll
;   for (int r = 0; r < 16; ++r) ps += p0[r];
; #pragma unroll
;   for (int r = 0; r < 16; ++r) ps += p1[r];
;   { auto rr = __builtin_amdgcn_permlane32_swap(__float_as_uint(ps), __float_as_uint(ps), false, false);
;     ps = __uint_as_float(rr[0]) + __uint_as_float(rr[1]); }
;   l_reg = l_reg * alpha + ps;
;     ...
;   PK4(p0, 0, pa0); PK4(p0, 8, pa1); PK4(p1, 0, pa2); PK4(p1, 8, pa3);
;     ...
; }
; template <int ND0>
; __device__ __forceinline__ void qkt(f32x16& p0, f32x16& p1, const char* Ks, const bf16x8* qr, int r32, int hi) {
;   p0 = f32x16{}; p1 = f32x16{};
; #pragma unroll
;   for (int d0 = 0; d0 < ND0; ++d0) { int cb = (d0 * 16 + hi * 8) * 2;
;     bf16x8 b0 = *reinterpret_cast<const bf16x8*>(Ks + KSWZ(r32, cb));
;     bf16x8 b1 = *reinterpret_cast<const bf16x8*>(Ks + KSWZ(32 + r32, cb));
;     p0 = __builtin_amdgcn_mfma_f32_32x32x16_bf16(b0, qr[d0], p0, 0, 0, 0);
;     p1 = __builtin_amdgcn_mfma_f32_32x32x16_bf16(b1, qr[d0], p1, 0, 0, 0); }
; }
; template <int ND0, int LDQ, int LDK, int LDO> ...
;     ...
;     SBAR(); qkt<ND0>(pA0, pA1, Kq0, qr, r32, hi);
;     finishSM(pB0, pB1, alB, l_reg, pa0, pa1, pa2, pa3); SBAR();
;     if (j + 3 < NT) SLOAD_A((j + 3) * KVBLK); SBAR();
.LBB0_153:
	v_mov_b32_e32 v242, 0x800
	ds_read_b128 v[238:241], v200 offset:32768
	ds_read_b128 v[234:237], v200 offset:40960
	ds_read_b128 v[146:149], v202 offset:32768
	ds_read_b128 v[150:153], v202 offset:40960
	ds_read_b128 v[154:157], v201 offset:32768
	ds_read_b128 v[158:161], v201 offset:40960
	v_exp_f32_e32 v245, v88
	v_exp_f32_e32 v246, v89
	s_waitcnt lgkmcnt(6)
	v_mfma_f32_32x32x16_bf16 v[96:111], v[64:67], v[114:117], 0
	v_exp_f32_e32 v247, v90
	v_exp_f32_e32 v231, v91
	v_exp_f32_e32 v243, v92
	v_exp_f32_e32 v252, v93
	v_exp_f32_e32 v253, v94
	v_exp_f32_e32 v95, v95
	v_mfma_f32_32x32x16_bf16 v[64:79], v[68:71], v[114:117], 0
	s_waitcnt lgkmcnt(4)
	v_mfma_f32_32x32x16_bf16 v[96:111], v[238:241], v[122:125], v[96:111]
	v_mfma_f32_32x32x16_bf16 v[64:79], v[234:237], v[122:125], v[64:79]
	ds_read_b128 v[234:237], v203 offset:32768
	ds_read_b128 v[238:241], v203 offset:40960
	s_waitcnt lgkmcnt(4)
	v_mfma_f32_32x32x16_bf16 v[96:111], v[146:149], v[142:145], v[96:111]
	v_mfma_f32_32x32x16_bf16 v[64:79], v[150:153], v[142:145], v[64:79]
	ds_read_b128 v[146:149], v204 offset:32768
	ds_read_b128 v[150:153], v204 offset:40960
	s_waitcnt lgkmcnt(4)
	v_mfma_f32_32x32x16_bf16 v[96:111], v[154:157], v[138:141], v[96:111]
	v_mfma_f32_32x32x16_bf16 v[64:79], v[158:161], v[138:141], v[64:79]
	ds_read_b128 v[154:157], v206 offset:32768
	ds_read_b128 v[158:161], v206 offset:40960
	s_waitcnt lgkmcnt(4)
	v_mfma_f32_32x32x16_bf16 v[96:111], v[234:237], v[134:137], v[96:111]
	v_mfma_f32_32x32x16_bf16 v[64:79], v[238:241], v[134:137], v[64:79]
	ds_read_b128 v[234:237], v205 offset:32768
	ds_read_b128 v[238:241], v205 offset:40960
	s_waitcnt lgkmcnt(4)
	v_mfma_f32_32x32x16_bf16 v[96:111], v[146:149], v[130:133], v[96:111]
	v_mfma_f32_32x32x16_bf16 v[64:79], v[150:153], v[130:133], v[64:79]
	s_waitcnt lgkmcnt(2)
	v_mfma_f32_32x32x16_bf16 v[96:111], v[154:157], v[126:129], v[96:111]
	v_mfma_f32_32x32x16_bf16 v[64:79], v[158:161], v[126:129], v[64:79]
	s_waitcnt lgkmcnt(0)
	v_mfma_f32_32x32x16_bf16 v[96:111], v[234:237], v[118:121], v[96:111]
	v_exp_f32_e32 v234, v80
	v_add_f32_e32 v80, v244, v226
	v_add_f32_e32 v80, v224, v80
	v_add_f32_e32 v80, v227, v80
	v_add_f32_e32 v80, v223, v80
	v_add_f32_e32 v80, v225, v80
	v_add_f32_e32 v80, v221, v80
	v_add_f32_e32 v80, v222, v80
	v_add_f32_e32 v80, v218, v80
	v_add_f32_e32 v80, v220, v80
	v_add_f32_e32 v80, v217, v80
	v_add_f32_e32 v80, v219, v80
	v_add_f32_e32 v80, v214, v80
	v_exp_f32_e32 v235, v81
	v_add_f32_e32 v80, v216, v80
	v_exp_f32_e32 v236, v82
	v_add_f32_e32 v80, v213, v80
	v_exp_f32_e32 v237, v83
	v_add_f32_e32 v80, v215, v80
	v_mfma_f32_32x32x16_bf16 v[64:79], v[238:241], v[118:121], v[64:79]
	v_exp_f32_e32 v238, v84
	v_add_f32_e32 v80, v234, v80
	v_exp_f32_e32 v239, v85
	v_add_f32_e32 v80, v235, v80
	v_exp_f32_e32 v240, v86
	v_add_f32_e32 v80, v236, v80
	v_exp_f32_e32 v241, v87
	v_add_f32_e32 v80, v237, v80
	v_add_f32_e32 v80, v238, v80
	v_add_f32_e32 v80, v239, v80
	v_add_f32_e32 v80, v240, v80
	v_add_f32_e32 v80, v241, v80
	v_add_f32_e32 v80, v245, v80
	v_add_f32_e32 v80, v246, v80
	v_add_f32_e32 v80, v247, v80
	v_add_f32_e32 v80, v231, v80
	v_add_f32_e32 v80, v243, v80
	v_add_f32_e32 v80, v252, v80
	v_add_f32_e32 v80, v253, v80
	v_add_f32_e32 v211, v95, v80
	v_mov_b32_e32 v212, v211
	v_cvt_pk_bf16_f32 v80, v226, v244
	v_cvt_pk_bf16_f32 v81, v224, v227
	v_cvt_pk_bf16_f32 v82, v223, v225
	v_cvt_pk_bf16_f32 v83, v221, v222
	v_cvt_pk_bf16_f32 v84, v218, v220
	v_cvt_pk_bf16_f32 v85, v217, v219
	v_cvt_pk_bf16_f32 v86, v214, v216
	v_cvt_pk_bf16_f32 v87, v213, v215
	v_cvt_pk_bf16_f32 v88, v234, v235
	v_cvt_pk_bf16_f32 v89, v236, v237
	v_cvt_pk_bf16_f32 v90, v238, v239
	v_cvt_pk_bf16_f32 v91, v240, v241
	v_cvt_pk_bf16_f32 v92, v245, v246
	v_cvt_pk_bf16_f32 v93, v247, v231
	v_cvt_pk_bf16_f32 v94, v243, v252
	v_cvt_pk_bf16_f32 v95, v253, v95
	v_permlane32_swap_b32_e32 v211, v212
	v_permlane32_swap_b32_e32 v80, v82
	v_permlane32_swap_b32_e32 v81, v83
	v_permlane32_swap_b32_e32 v84, v86
	v_permlane32_swap_b32_e32 v85, v87
	v_permlane32_swap_b32_e32 v88, v90
	v_permlane32_swap_b32_e32 v89, v91
	v_permlane32_swap_b32_e32 v92, v94
	v_permlane32_swap_b32_e32 v93, v95
	s_add_i32 s39, s39, 2
	s_cmp_ge_u32 s39, s38
	s_cselect_b64 s[4:5], -1, 0
	s_and_b64 vcc, exec, s[4:5]
	s_cbranch_vccnz .Lgqa_pf_skip
	v_add_co_u32_e32 v146, vcc, 0xfffe8000, v188
	s_nop 1
	v_addc_co_u32_e32 v147, vcc, -1, v189, vcc
	global_load_dwordx4 v[158:161], v[146:147], off
	global_load_dwordx4 v[150:153], v[146:147], off offset:-512
	global_load_dwordx4 v[154:157], v[188:189], off
	global_load_dwordx4 v[146:149], v[188:189], off offset:-512
